# GEMM unit boundaries: the two wave halves no longer re-align before the epilogue and re-stagger after it (two barriers per unit removed); each half runs its epilogue inside its own one-barrier-offset
# baseline (speedup 1.0000x reference)
; #define PG8_BAR __builtin_amdgcn_s_barrier()
; template <class Epi>
; __device__ __forceinline__ void gemm_phase(LAS unsigned char* lds, const Gemm g, const TabSched& S, const Epi& E) {
;     ...
;         if (wr == 0) PG8_BAR;
.Lk1_exit:
	s_andn2_b64 vcc, s[6:7], s[44:45]
	s_cbranch_vccz .LBB0_420

; #define PG8_BAR __builtin_amdgcn_s_barrier()
; template <class Epi>
; __device__ __forceinline__ void gemm_phase(LAS unsigned char* lds, const Gemm g, const TabSched& S, const Epi& E) {
;     ...
;         if (wr == 0) PG8_BAR;
;     ...
;         for (int a = 0; a < 2; ++a)
; #pragma unroll
;             for (int b = 0; b < 2; ++b)
; #pragma unroll
;                 for (int m = 0; m < 4; ++m)
; #pragma unroll
;                     for (int n = 0; n < 2; ++n) acc[a][b][m][n] = (f32x4){0.f, 0.f, 0.f, 0.f};
.LBB0_425:
	s_waitcnt vmcnt(0)
	v_mov_b32_e32 v135, 0
	v_mov_b32_e32 v134, v135
	v_mov_b32_e32 v133, v135
	v_mov_b32_e32 v132, v135
	v_mov_b32_e32 v131, v135
	v_mov_b32_e32 v130, v135
	v_mov_b32_e32 v129, v135
	v_mov_b32_e32 v128, v135
	v_mov_b32_e32 v127, v135
	v_mov_b32_e32 v126, v135
	v_mov_b32_e32 v125, v135
	v_mov_b32_e32 v124, v135
	v_mov_b32_e32 v123, v135
	v_mov_b32_e32 v122, v135
	v_mov_b32_e32 v121, v135
	v_mov_b32_e32 v120, v135
	v_mov_b32_e32 v119, v135
	v_mov_b32_e32 v118, v135
	v_mov_b32_e32 v117, v135
	v_mov_b32_e32 v116, v135
	v_mov_b32_e32 v115, v135
	v_mov_b32_e32 v114, v135
	v_mov_b32_e32 v113, v135
	v_mov_b32_e32 v112, v135
	v_mov_b32_e32 v111, v135
	v_mov_b32_e32 v110, v135
	v_mov_b32_e32 v109, v135
	v_mov_b32_e32 v108, v135
	v_mov_b32_e32 v107, v135
	v_mov_b32_e32 v106, v135
	v_mov_b32_e32 v105, v135
	v_mov_b32_e32 v104, v135
	v_mov_b32_e32 v103, v135
	v_mov_b32_e32 v102, v135
	v_mov_b32_e32 v101, v135
	v_mov_b32_e32 v100, v135
	v_mov_b32_e32 v99, v135
	v_mov_b32_e32 v98, v135
	v_mov_b32_e32 v97, v135
	v_mov_b32_e32 v96, v135
	v_mov_b32_e32 v95, v135
	v_mov_b32_e32 v94, v135
	v_mov_b32_e32 v93, v135
	v_mov_b32_e32 v92, v135
	v_mov_b32_e32 v91, v135
	v_mov_b32_e32 v90, v135
	v_mov_b32_e32 v89, v135
	v_mov_b32_e32 v88, v135
	v_mov_b32_e32 v87, v135
	v_mov_b32_e32 v86, v135
	v_mov_b32_e32 v85, v135
	v_mov_b32_e32 v84, v135
	v_mov_b32_e32 v83, v135
	v_mov_b32_e32 v82, v135
	v_mov_b32_e32 v81, v135
	v_mov_b32_e32 v80, v135
	v_mov_b32_e32 v79, v135
	v_mov_b32_e32 v78, v135
	v_mov_b32_e32 v77, v135
	v_mov_b32_e32 v76, v135
	v_mov_b32_e32 v75, v135
	v_mov_b32_e32 v74, v135
	v_mov_b32_e32 v73, v135
	v_mov_b32_e32 v72, v135
	v_mov_b32_e32 v71, v135
	v_mov_b32_e32 v70, v135
	v_mov_b32_e32 v69, v135
	v_mov_b32_e32 v68, v135
	v_mov_b32_e32 v67, v135
	v_mov_b32_e32 v66, v135
	v_mov_b32_e32 v65, v135
	v_mov_b32_e32 v64, v135
	v_mov_b32_e32 v63, v135
	v_mov_b32_e32 v62, v135
	v_mov_b32_e32 v61, v135
	v_mov_b32_e32 v60, v135
	v_mov_b32_e32 v59, v135
	v_mov_b32_e32 v58, v135
	v_mov_b32_e32 v57, v135
	v_mov_b32_e32 v56, v135
	v_mov_b32_e32 v55, v135
	v_mov_b32_e32 v54, v135
	v_mov_b32_e32 v53, v135
	v_mov_b32_e32 v52, v135
	v_mov_b32_e32 v51, v135
	v_mov_b32_e32 v50, v135
	v_mov_b32_e32 v49, v135
	v_mov_b32_e32 v48, v135
	v_mov_b32_e32 v47, v135
	v_mov_b32_e32 v46, v135
	v_mov_b32_e32 v45, v135
	v_mov_b32_e32 v44, v135
	v_mov_b32_e32 v43, v135
	v_mov_b32_e32 v42, v135
	v_mov_b32_e32 v41, v135
	v_mov_b32_e32 v40, v135
	v_mov_b32_e32 v39, v135
	v_mov_b32_e32 v38, v135
	v_mov_b32_e32 v37, v135
	v_mov_b32_e32 v36, v135
	v_mov_b32_e32 v35, v135
	v_mov_b32_e32 v34, v135
	v_mov_b32_e32 v33, v135
	v_mov_b32_e32 v32, v135
	v_mov_b32_e32 v31, v135
	v_mov_b32_e32 v30, v135
	v_mov_b32_e32 v29, v135
	v_mov_b32_e32 v28, v135
	v_mov_b32_e32 v27, v135
	v_mov_b32_e32 v26, v135
	v_mov_b32_e32 v25, v135
	v_mov_b32_e32 v24, v135
	v_mov_b32_e32 v23, v135
	v_mov_b32_e32 v22, v135
	v_mov_b32_e32 v21, v135
	v_mov_b32_e32 v20, v135
	v_mov_b32_e32 v19, v135
	v_mov_b32_e32 v18, v135
	v_mov_b32_e32 v17, v135
	v_mov_b32_e32 v16, v135
	v_mov_b32_e32 v15, v135
	v_mov_b32_e32 v14, v135
	v_mov_b32_e32 v13, v135
	v_mov_b32_e32 v12, v135
	v_mov_b32_e32 v11, v135
	v_mov_b32_e32 v10, v135
	v_mov_b32_e32 v9, v135
	v_mov_b32_e32 v8, v135
	s_andn2_b64 vcc, s[6:7], s[44:45]
	s_cbranch_vccnz .LBB0_419
	s_branch .LBB0_420

; #define PG8_BAR __builtin_amdgcn_s_barrier()
; template <class Epi>
; __device__ __forceinline__ void gemm_phase(LAS unsigned char* lds, const Gemm g, const TabSched& S, const Epi& E) {
;     ...
;         cur = nxt; cA = nA; cB = nB; ++ui;
;         if (wr == 1) PG8_BAR;
.LBB0_738:
	s_branch .LBB0_410
	s_cbranch_vccnz .LBB0_410
	s_barrier
	s_branch .LBB0_410
